# v81 + P5 without the per-unit ALIGN_EPI barrier pair (leading half's epilogue overlaps the trailing half's last MFMA block; last unit still aligns)
# baseline (speedup 1.0000x reference)
.LBB0_1080:
	ds_read_b128 v[150:153], v147
	ds_read_b128 v[154:157], v147 offset:1024
	ds_read_b128 v[158:161], v147 offset:2048
	ds_read_b128 v[162:165], v147 offset:3072
	ds_read_b128 v[166:169], v148
	ds_read_b128 v[170:173], v148 offset:1024
	ds_read_b128 v[174:177], v148 offset:2048
	ds_read_b128 v[180:183], v148 offset:3072
	s_add_u32 s36, s34, 0xfffc0080
	s_addc_u32 s37, s35, -1
	s_cmp_eq_u32 s64, 12
	s_cselect_b32 s39, s27, s37
	s_cselect_b32 s38, s60, s36
	s_cselect_b32 s37, s25, s63
	s_cselect_b32 s36, s61, s62
	v_lshl_add_u64 v[216:217], s[34:35], 0, v[136:137]
	s_add_i32 m0, s42, 0xc000
	ds_read_b128 v[184:187], v149
	ds_read_b128 v[188:191], v149 offset:1024
	ds_read_b128 v[192:195], v149 offset:2048
	ds_read_b128 v[196:199], v149 offset:3072
	ds_read_b128 v[200:203], v149 offset:4096
	ds_read_b128 v[204:207], v149 offset:5120
	ds_read_b128 v[208:211], v149 offset:6144
	ds_read_b128 v[212:215], v149 offset:7168
	global_load_lds_dwordx4 v[216:217], off
	v_lshl_add_u64 v[216:217], s[34:35], 0, v[138:139]
	s_add_i32 m0, s42, 0xe000
	s_nop 0
	global_load_lds_dwordx4 v[216:217], off
	s_waitcnt vmcnt(8)
	s_waitcnt lgkmcnt(0)
	s_barrier
	s_setprio 1
	s_waitcnt lgkmcnt(0)
	v_mfma_f32_16x16x32_bf16 v[124:127], v[150:153], v[184:187], v[124:127]
	v_mfma_f32_16x16x32_bf16 v[120:123], v[158:161], v[184:187], v[120:123]
	v_mfma_f32_16x16x32_bf16 v[108:111], v[150:153], v[192:195], v[108:111]
	v_mfma_f32_16x16x32_bf16 v[104:107], v[158:161], v[192:195], v[104:107]
	v_mfma_f32_16x16x32_bf16 v[92:95], v[150:153], v[200:203], v[92:95]
	v_mfma_f32_16x16x32_bf16 v[88:91], v[158:161], v[200:203], v[88:91]
	v_mfma_f32_16x16x32_bf16 v[76:79], v[150:153], v[208:211], v[76:79]
	v_mfma_f32_16x16x32_bf16 v[72:75], v[158:161], v[208:211], v[72:75]
	v_mfma_f32_16x16x32_bf16 v[124:127], v[154:157], v[188:191], v[124:127]
	v_mfma_f32_16x16x32_bf16 v[120:123], v[162:165], v[188:191], v[120:123]
	v_mfma_f32_16x16x32_bf16 v[108:111], v[154:157], v[196:199], v[108:111]
	v_mfma_f32_16x16x32_bf16 v[104:107], v[162:165], v[196:199], v[104:107]
	v_mfma_f32_16x16x32_bf16 v[92:95], v[154:157], v[204:207], v[92:95]
	v_mfma_f32_16x16x32_bf16 v[88:91], v[162:165], v[204:207], v[88:91]
	v_mfma_f32_16x16x32_bf16 v[76:79], v[154:157], v[212:215], v[76:79]
	v_mfma_f32_16x16x32_bf16 v[72:75], v[162:165], v[212:215], v[72:75]
	s_setprio 0
	s_setprio 1
	v_mfma_f32_16x16x32_bf16 v[116:119], v[166:169], v[184:187], v[116:119]
	v_mfma_f32_16x16x32_bf16 v[112:115], v[174:177], v[184:187], v[112:115]
	v_mfma_f32_16x16x32_bf16 v[100:103], v[166:169], v[192:195], v[100:103]
	v_mfma_f32_16x16x32_bf16 v[96:99], v[174:177], v[192:195], v[96:99]
	v_mfma_f32_16x16x32_bf16 v[84:87], v[166:169], v[200:203], v[84:87]
	v_mfma_f32_16x16x32_bf16 v[80:83], v[174:177], v[200:203], v[80:83]
	v_mfma_f32_16x16x32_bf16 v[68:71], v[166:169], v[208:211], v[68:71]
	v_mfma_f32_16x16x32_bf16 v[64:67], v[174:177], v[208:211], v[64:67]
	v_mfma_f32_16x16x32_bf16 v[116:119], v[170:173], v[188:191], v[116:119]
	v_mfma_f32_16x16x32_bf16 v[112:115], v[180:183], v[188:191], v[112:115]
	v_mfma_f32_16x16x32_bf16 v[100:103], v[170:173], v[196:199], v[100:103]
	v_mfma_f32_16x16x32_bf16 v[96:99], v[180:183], v[196:199], v[96:99]
	v_mfma_f32_16x16x32_bf16 v[84:87], v[170:173], v[204:207], v[84:87]
	v_mfma_f32_16x16x32_bf16 v[80:83], v[180:183], v[204:207], v[80:83]
	v_mfma_f32_16x16x32_bf16 v[68:71], v[170:173], v[212:215], v[68:71]
	v_mfma_f32_16x16x32_bf16 v[64:67], v[180:183], v[212:215], v[64:67]
	s_setprio 0
	s_barrier
	s_add_i32 s65, s52, s41
	v_lshl_add_u64 v[216:217], s[36:37], 0, v[132:133]
	s_mov_b32 m0, s65
	ds_read_b128 v[184:187], v149 offset:16384
	ds_read_b128 v[188:191], v149 offset:17408
	ds_read_b128 v[192:195], v149 offset:18432
	ds_read_b128 v[196:199], v149 offset:19456
	ds_read_b128 v[200:203], v149 offset:20480
	ds_read_b128 v[204:207], v149 offset:21504
	ds_read_b128 v[208:211], v149 offset:22528
	ds_read_b128 v[212:215], v149 offset:23552
	global_load_lds_dwordx4 v[216:217], off
	s_add_i32 m0, s65, 0x2000
	s_add_u32 s66, s36, 0x40000
	v_lshl_add_u64 v[218:219], s[36:37], 0, v[128:129]
	s_addc_u32 s67, s37, 0
	s_add_i32 s65, s53, s41
	global_load_lds_dwordx4 v[218:219], off
	v_lshl_add_u64 v[220:221], s[66:67], 0, v[132:133]
	s_mov_b32 m0, s65
	v_lshl_add_u64 v[222:223], s[38:39], 0, v[130:131]
	global_load_lds_dwordx4 v[220:221], off
	v_lshl_add_u64 v[220:221], s[66:67], 0, v[128:129]
	s_add_i32 m0, s65, 0x2000
	s_nop 0
	global_load_lds_dwordx4 v[220:221], off
	v_lshl_add_u64 v[220:221], s[38:39], 0, v[134:135]
	s_mov_b32 m0, s42
	s_nop 0
	global_load_lds_dwordx4 v[220:221], off
	s_mov_b32 m0, s43
	s_nop 0
	global_load_lds_dwordx4 v[222:223], off
	s_waitcnt vmcnt(8)
	s_waitcnt lgkmcnt(0)
	s_barrier
	s_setprio 1
	s_waitcnt lgkmcnt(0)
	v_mfma_f32_16x16x32_bf16 v[60:63], v[150:153], v[184:187], v[60:63]
	v_mfma_f32_16x16x32_bf16 v[56:59], v[158:161], v[184:187], v[56:59]
	v_mfma_f32_16x16x32_bf16 v[44:47], v[150:153], v[192:195], v[44:47]
	v_mfma_f32_16x16x32_bf16 v[40:43], v[158:161], v[192:195], v[40:43]
	v_mfma_f32_16x16x32_bf16 v[28:31], v[150:153], v[200:203], v[28:31]
	v_mfma_f32_16x16x32_bf16 v[24:27], v[158:161], v[200:203], v[24:27]
	v_mfma_f32_16x16x32_bf16 v[12:15], v[150:153], v[208:211], v[12:15]
	v_mfma_f32_16x16x32_bf16 v[8:11], v[158:161], v[208:211], v[8:11]
	v_mfma_f32_16x16x32_bf16 v[60:63], v[154:157], v[188:191], v[60:63]
	v_mfma_f32_16x16x32_bf16 v[56:59], v[162:165], v[188:191], v[56:59]
	v_mfma_f32_16x16x32_bf16 v[44:47], v[154:157], v[196:199], v[44:47]
	v_mfma_f32_16x16x32_bf16 v[40:43], v[162:165], v[196:199], v[40:43]
	v_mfma_f32_16x16x32_bf16 v[28:31], v[154:157], v[204:207], v[28:31]
	v_mfma_f32_16x16x32_bf16 v[24:27], v[162:165], v[204:207], v[24:27]
	v_mfma_f32_16x16x32_bf16 v[12:15], v[154:157], v[212:215], v[12:15]
	v_mfma_f32_16x16x32_bf16 v[8:11], v[162:165], v[212:215], v[8:11]
	s_setprio 0
	s_setprio 1
	v_mfma_f32_16x16x32_bf16 v[52:55], v[166:169], v[184:187], v[52:55]
	v_mfma_f32_16x16x32_bf16 v[48:51], v[174:177], v[184:187], v[48:51]
	v_mfma_f32_16x16x32_bf16 v[36:39], v[166:169], v[192:195], v[36:39]
	v_mfma_f32_16x16x32_bf16 v[32:35], v[174:177], v[192:195], v[32:35]
	v_mfma_f32_16x16x32_bf16 v[20:23], v[166:169], v[200:203], v[20:23]
	v_mfma_f32_16x16x32_bf16 v[16:19], v[174:177], v[200:203], v[16:19]
	v_mfma_f32_16x16x32_bf16 v[4:7], v[166:169], v[208:211], v[4:7]
	v_mfma_f32_16x16x32_bf16 v[0:3], v[174:177], v[208:211], v[0:3]
	v_mfma_f32_16x16x32_bf16 v[52:55], v[170:173], v[188:191], v[52:55]
	v_mfma_f32_16x16x32_bf16 v[48:51], v[180:183], v[188:191], v[48:51]
	v_mfma_f32_16x16x32_bf16 v[36:39], v[170:173], v[196:199], v[36:39]
	v_mfma_f32_16x16x32_bf16 v[32:35], v[180:183], v[196:199], v[32:35]
	v_mfma_f32_16x16x32_bf16 v[20:23], v[170:173], v[204:207], v[20:23]
	v_mfma_f32_16x16x32_bf16 v[16:19], v[180:183], v[204:207], v[16:19]
	v_mfma_f32_16x16x32_bf16 v[4:7], v[170:173], v[212:215], v[4:7]
	v_mfma_f32_16x16x32_bf16 v[0:3], v[180:183], v[212:215], v[0:3]
	s_setprio 0
	s_barrier
	s_add_i32 s65, 0, 0x18000
	s_add_i32 s66, 0, 0x1c000
	v_add_u32_e32 v162, s65, v145
	v_add_u32_e32 v178, s66, v145
	ds_read_b128 v[150:153], v162
	ds_read_b128 v[154:157], v162 offset:1024
	ds_read_b128 v[158:161], v162 offset:2048
	ds_read_b128 v[162:165], v162 offset:3072
	ds_read_b128 v[166:169], v178
	ds_read_b128 v[170:173], v178 offset:1024
	ds_read_b128 v[174:177], v178 offset:2048
	ds_read_b128 v[180:183], v178 offset:3072
	s_add_u32 s38, s38, 0x40000
	s_addc_u32 s39, s39, 0
	s_mov_b32 m0, s44
	v_lshl_add_u64 v[224:225], s[38:39], 0, v[134:135]
	ds_read_b128 v[184:187], v149 offset:32768
	ds_read_b128 v[188:191], v149 offset:33792
	ds_read_b128 v[192:195], v149 offset:34816
	ds_read_b128 v[196:199], v149 offset:35840
	ds_read_b128 v[200:203], v149 offset:36864
	ds_read_b128 v[204:207], v149 offset:37888
	ds_read_b128 v[208:211], v149 offset:38912
	ds_read_b128 v[212:215], v149 offset:39936
	global_load_lds_dwordx4 v[224:225], off
	v_lshl_add_u64 v[224:225], s[38:39], 0, v[130:131]
	s_mov_b32 m0, s45
	s_nop 0
	global_load_lds_dwordx4 v[224:225], off
	s_waitcnt vmcnt(8)
	s_waitcnt lgkmcnt(0)
	s_barrier
	s_setprio 1
	s_waitcnt lgkmcnt(0)
	v_mfma_f32_16x16x32_bf16 v[124:127], v[150:153], v[184:187], v[124:127]
	v_mfma_f32_16x16x32_bf16 v[120:123], v[158:161], v[184:187], v[120:123]
	v_mfma_f32_16x16x32_bf16 v[108:111], v[150:153], v[192:195], v[108:111]
	v_mfma_f32_16x16x32_bf16 v[104:107], v[158:161], v[192:195], v[104:107]
	v_mfma_f32_16x16x32_bf16 v[92:95], v[150:153], v[200:203], v[92:95]
	v_mfma_f32_16x16x32_bf16 v[88:91], v[158:161], v[200:203], v[88:91]
	v_mfma_f32_16x16x32_bf16 v[76:79], v[150:153], v[208:211], v[76:79]
	v_mfma_f32_16x16x32_bf16 v[72:75], v[158:161], v[208:211], v[72:75]
	v_mfma_f32_16x16x32_bf16 v[124:127], v[154:157], v[188:191], v[124:127]
	v_mfma_f32_16x16x32_bf16 v[120:123], v[162:165], v[188:191], v[120:123]
	v_mfma_f32_16x16x32_bf16 v[108:111], v[154:157], v[196:199], v[108:111]
	v_mfma_f32_16x16x32_bf16 v[104:107], v[162:165], v[196:199], v[104:107]
	v_mfma_f32_16x16x32_bf16 v[92:95], v[154:157], v[204:207], v[92:95]
	v_mfma_f32_16x16x32_bf16 v[88:91], v[162:165], v[204:207], v[88:91]
	v_mfma_f32_16x16x32_bf16 v[76:79], v[154:157], v[212:215], v[76:79]
	v_mfma_f32_16x16x32_bf16 v[72:75], v[162:165], v[212:215], v[72:75]
	s_setprio 0
	s_setprio 1
	v_mfma_f32_16x16x32_bf16 v[116:119], v[166:169], v[184:187], v[116:119]
	v_mfma_f32_16x16x32_bf16 v[112:115], v[174:177], v[184:187], v[112:115]
	v_mfma_f32_16x16x32_bf16 v[100:103], v[166:169], v[192:195], v[100:103]
	v_mfma_f32_16x16x32_bf16 v[96:99], v[174:177], v[192:195], v[96:99]
	v_mfma_f32_16x16x32_bf16 v[84:87], v[166:169], v[200:203], v[84:87]
	v_mfma_f32_16x16x32_bf16 v[80:83], v[174:177], v[200:203], v[80:83]
	v_mfma_f32_16x16x32_bf16 v[68:71], v[166:169], v[208:211], v[68:71]
	v_mfma_f32_16x16x32_bf16 v[64:67], v[174:177], v[208:211], v[64:67]
	v_mfma_f32_16x16x32_bf16 v[116:119], v[170:173], v[188:191], v[116:119]
	v_mfma_f32_16x16x32_bf16 v[112:115], v[180:183], v[188:191], v[112:115]
	v_mfma_f32_16x16x32_bf16 v[100:103], v[170:173], v[196:199], v[100:103]
	v_mfma_f32_16x16x32_bf16 v[96:99], v[180:183], v[196:199], v[96:99]
	v_mfma_f32_16x16x32_bf16 v[84:87], v[170:173], v[204:207], v[84:87]
	v_mfma_f32_16x16x32_bf16 v[80:83], v[180:183], v[204:207], v[80:83]
	v_mfma_f32_16x16x32_bf16 v[68:71], v[170:173], v[212:215], v[68:71]
	v_mfma_f32_16x16x32_bf16 v[64:67], v[180:183], v[212:215], v[64:67]
	s_setprio 0
	s_barrier
	s_add_i32 s38, s65, s41
	v_lshl_add_u64 v[216:217], v[216:217], 0, s[6:7]
	s_mov_b32 m0, s38
	ds_read_b128 v[184:187], v149 offset:49152
	ds_read_b128 v[188:191], v149 offset:50176
	ds_read_b128 v[192:195], v149 offset:51200
	ds_read_b128 v[196:199], v149 offset:52224
	ds_read_b128 v[200:203], v149 offset:53248
	ds_read_b128 v[204:207], v149 offset:54272
	ds_read_b128 v[208:211], v149 offset:55296
	ds_read_b128 v[212:215], v149 offset:56320
	global_load_lds_dwordx4 v[216:217], off
	s_add_i32 m0, s38, 0x2000
	s_add_u32 s36, s36, 0x40080
	v_lshl_add_u64 v[216:217], v[218:219], 0, s[6:7]
	s_addc_u32 s37, s37, 0
	s_add_i32 s38, s66, s41
	global_load_lds_dwordx4 v[216:217], off
	v_lshl_add_u64 v[216:217], s[36:37], 0, v[132:133]
	s_mov_b32 m0, s38
	s_nop 0
	global_load_lds_dwordx4 v[216:217], off
	v_lshl_add_u64 v[216:217], s[36:37], 0, v[128:129]
	s_add_i32 m0, s38, 0x2000
	s_nop 0
	global_load_lds_dwordx4 v[216:217], off
	v_lshl_add_u64 v[216:217], v[220:221], 0, s[6:7]
	s_mov_b32 m0, s47
	s_nop 0
	global_load_lds_dwordx4 v[216:217], off
	v_lshl_add_u64 v[216:217], v[222:223], 0, s[6:7]
	s_mov_b32 m0, s48
	s_nop 0
	global_load_lds_dwordx4 v[216:217], off
	s_waitcnt vmcnt(8)
	s_waitcnt lgkmcnt(0)
	s_barrier
	s_setprio 1
	s_waitcnt lgkmcnt(0)
	v_mfma_f32_16x16x32_bf16 v[60:63], v[150:153], v[184:187], v[60:63]
	v_mfma_f32_16x16x32_bf16 v[56:59], v[158:161], v[184:187], v[56:59]
	v_mfma_f32_16x16x32_bf16 v[44:47], v[150:153], v[192:195], v[44:47]
	v_mfma_f32_16x16x32_bf16 v[40:43], v[158:161], v[192:195], v[40:43]
	v_mfma_f32_16x16x32_bf16 v[28:31], v[150:153], v[200:203], v[28:31]
	v_mfma_f32_16x16x32_bf16 v[24:27], v[158:161], v[200:203], v[24:27]
	v_mfma_f32_16x16x32_bf16 v[12:15], v[150:153], v[208:211], v[12:15]
	v_mfma_f32_16x16x32_bf16 v[8:11], v[158:161], v[208:211], v[8:11]
	v_mfma_f32_16x16x32_bf16 v[60:63], v[154:157], v[188:191], v[60:63]
	v_mfma_f32_16x16x32_bf16 v[56:59], v[162:165], v[188:191], v[56:59]
	v_mfma_f32_16x16x32_bf16 v[44:47], v[154:157], v[196:199], v[44:47]
	v_mfma_f32_16x16x32_bf16 v[40:43], v[162:165], v[196:199], v[40:43]
	v_mfma_f32_16x16x32_bf16 v[28:31], v[154:157], v[204:207], v[28:31]
	v_mfma_f32_16x16x32_bf16 v[24:27], v[162:165], v[204:207], v[24:27]
	v_mfma_f32_16x16x32_bf16 v[12:15], v[154:157], v[212:215], v[12:15]
	v_mfma_f32_16x16x32_bf16 v[8:11], v[162:165], v[212:215], v[8:11]
	s_setprio 0
	s_setprio 1
	v_mfma_f32_16x16x32_bf16 v[52:55], v[166:169], v[184:187], v[52:55]
	v_mfma_f32_16x16x32_bf16 v[48:51], v[174:177], v[184:187], v[48:51]
	v_mfma_f32_16x16x32_bf16 v[36:39], v[166:169], v[192:195], v[36:39]
	v_mfma_f32_16x16x32_bf16 v[32:35], v[174:177], v[192:195], v[32:35]
	v_mfma_f32_16x16x32_bf16 v[20:23], v[166:169], v[200:203], v[20:23]
	v_mfma_f32_16x16x32_bf16 v[16:19], v[174:177], v[200:203], v[16:19]
	v_mfma_f32_16x16x32_bf16 v[4:7], v[166:169], v[208:211], v[4:7]
	v_mfma_f32_16x16x32_bf16 v[0:3], v[174:177], v[208:211], v[0:3]
	v_mfma_f32_16x16x32_bf16 v[52:55], v[170:173], v[188:191], v[52:55]
	v_mfma_f32_16x16x32_bf16 v[48:51], v[180:183], v[188:191], v[48:51]
	v_mfma_f32_16x16x32_bf16 v[36:39], v[170:173], v[196:199], v[36:39]
	v_mfma_f32_16x16x32_bf16 v[32:35], v[180:183], v[196:199], v[32:35]
	v_mfma_f32_16x16x32_bf16 v[20:23], v[170:173], v[204:207], v[20:23]
	v_mfma_f32_16x16x32_bf16 v[16:19], v[180:183], v[204:207], v[16:19]
	v_mfma_f32_16x16x32_bf16 v[4:7], v[170:173], v[212:215], v[4:7]
	v_mfma_f32_16x16x32_bf16 v[0:3], v[180:183], v[212:215], v[0:3]
	s_setprio 0
	s_barrier
	s_add_i32 s64, s64, 2
	s_add_u32 s34, s34, 0x100
	s_addc_u32 s35, s35, 0
	s_add_u32 s62, s62, 0x100
	s_addc_u32 s63, s63, 0
	s_cmp_gt_u32 s64, 13
	s_cbranch_scc0 .LBB0_1080
	s_and_b64 vcc, exec, s[8:9]
	s_cbranch_vccz .LBB0_1083
	s_and_b64 vcc, exec, s[4:5]
	s_cbranch_vccnz .LBB0_1083
	s_barrier
.LBB0_1083:
	v_lshl_add_u32 v150, s59, 8, v144
	v_ashrrev_i32_e32 v151, 31, v150
	v_lshl_add_u64 v[152:153], v[150:151], 2, s[16:17]
	global_load_dword v158, v[152:153], off
	v_max_f32_e32 v157, v124, v124
	v_or_b32_e32 v124, 16, v150
	v_max_f32_e32 v159, v125, v125
	v_ashrrev_i32_e32 v125, 31, v124
	v_max_f32_e32 v161, v112, v112
	v_max_f32_e32 v162, v113, v113
	v_lshl_add_u64 v[112:113], v[124:125], 2, s[16:17]
	global_load_dword v163, v[112:113], off
	v_lshl_or_b32 v154, s58, 8, v146
	v_max_f32_e32 v160, v126, v126
	v_max_f32_e32 v127, v127, v127
	v_or_b32_e32 v126, 32, v150
	v_or_b32_e32 v156, 48, v150
	v_max_f32_e32 v120, v120, v120
	v_max_f32_e32 v121, v121, v121
	v_max_f32_e32 v122, v122, v122
	v_max_f32_e32 v123, v123, v123
	v_max_f32_e32 v116, v116, v116
	v_max_f32_e32 v114, v114, v114
	v_ashrrev_i32_e32 v155, 31, v154
	v_max_f32_e32 v164, 0, v157
	v_max_f32_e32 v168, 0, v127
	v_ashrrev_i32_e32 v127, 31, v126
	v_ashrrev_i32_e32 v157, 31, v156
	v_max_f32_e32 v165, 0, v120
	v_max_f32_e32 v166, 0, v121
	v_max_f32_e32 v167, 0, v122
	v_max_f32_e32 v169, 0, v123
	v_max_f32_e32 v170, 0, v116
	v_max_f32_e32 v171, 0, v114
	v_lshlrev_b64 v[112:113], 13, v[150:151]
	v_lshlrev_b64 v[150:151], 1, v[154:155]
	v_lshl_add_u64 v[120:121], v[126:127], 2, s[16:17]
	v_lshl_add_u64 v[122:123], v[156:157], 2, s[16:17]
	global_load_dword v154, v[152:153], off offset:512
	global_load_dword v155, v[152:153], off offset:576
	global_load_dword v116, v[152:153], off offset:640
	global_load_dword v172, v[120:121], off
	global_load_dword v173, v[122:123], off
	global_load_dword v114, v[152:153], off offset:704
	v_max_f32_e32 v118, v118, v118
	v_max_f32_e32 v159, 0, v159
	v_max_f32_e32 v160, 0, v160
	v_max_f32_e32 v118, 0, v118
	v_max_f32_e32 v115, v115, v115
	v_max_f32_e32 v117, v117, v117
	v_max_f32_e32 v115, 0, v115
	v_max_f32_e32 v104, v104, v104
	v_max_f32_e32 v161, 0, v161
	v_max_f32_e32 v117, 0, v117
	v_max_f32_e32 v162, 0, v162
	v_lshl_add_u64 v[112:113], s[92:93], 0, v[112:113]
	v_max_f32_e32 v104, 0, v104
	v_max_f32_e32 v105, v105, v105
	v_max_f32_e32 v106, v106, v106
	v_lshl_add_u64 v[112:113], v[112:113], 0, v[150:151]
	v_max_f32_e32 v105, 0, v105
	v_max_f32_e32 v106, 0, v106
	v_max_f32_e32 v108, v108, v108
	v_max_f32_e32 v107, v107, v107
	v_max_f32_e32 v108, 0, v108
	v_max_f32_e32 v107, 0, v107
	v_max_f32_e32 v96, v96, v96
	v_max_f32_e32 v97, v97, v97
	v_max_f32_e32 v98, v98, v98
	v_max_f32_e32 v96, 0, v96
	v_max_f32_e32 v97, 0, v97
	v_max_f32_e32 v98, 0, v98
	v_max_f32_e32 v100, v100, v100
	v_max_f32_e32 v99, v99, v99
	v_max_f32_e32 v100, 0, v100
	v_max_f32_e32 v99, 0, v99
	v_max_f32_e32 v88, v88, v88
	v_max_f32_e32 v88, 0, v88
	v_max_f32_e32 v89, v89, v89
	v_max_f32_e32 v90, v90, v90
	v_max_f32_e32 v89, 0, v89
	v_max_f32_e32 v90, 0, v90
	v_max_f32_e32 v92, v92, v92
	v_max_f32_e32 v91, v91, v91
	v_max_f32_e32 v92, 0, v92
	v_max_f32_e32 v91, 0, v91
	v_max_f32_e32 v80, v80, v80
	v_max_f32_e32 v81, v81, v81
	s_waitcnt vmcnt(0)
	v_mul_f32_e32 v120, v164, v158
	v_mul_f32_e32 v121, v165, v158
	v_mul_f32_e32 v122, v159, v158
	v_mul_f32_e32 v123, v166, v158
	v_mul_f32_e32 v152, v160, v158
	v_mul_f32_e32 v153, v167, v158
	v_mul_f32_e32 v159, v168, v158
	v_mul_f32_e32 v160, v169, v158
	v_mul_f32_e32 v164, v170, v158
	v_mul_f32_e32 v118, v118, v158
	v_mul_f32_e32 v166, v121, v121
	v_mul_f32_e32 v121, v122, v122
	v_mul_f32_e32 v122, v123, v123
	v_mul_f32_e32 v123, v152, v152
	v_mul_f32_e32 v152, v153, v153
	v_mul_f32_e32 v153, v159, v159
	v_mul_f32_e32 v159, v160, v160
	v_mul_f32_e32 v160, v164, v164
	v_mul_f32_e32 v164, v118, v118
	v_max_f32_e32 v118, v119, v119
	v_max_f32_e32 v118, 0, v118
	v_mul_f32_e32 v120, v120, v120
	v_mul_f32_e32 v118, v118, v158
	v_mul_f32_e32 v115, v115, v158
	v_mul_f32_e32 v161, v161, v158
	v_mul_f32_e32 v117, v117, v158
	v_mul_f32_e32 v162, v162, v158
	v_mul_f32_e32 v165, v171, v158
	v_cvt_pk_bf16_f32 v120, v120, v121
	v_cvt_pk_bf16_f32 v121, v123, v153
	v_mul_f32_e32 v119, v118, v118
	v_mul_f32_e32 v115, v115, v115
	v_mul_f32_e32 v104, v104, v163
	v_mul_f32_e32 v161, v161, v161
	v_mul_f32_e32 v117, v117, v117
	v_mul_f32_e32 v162, v162, v162
	v_mul_f32_e32 v165, v165, v165
	v_cvt_pk_bf16_f32 v122, v166, v122
	v_cvt_pk_bf16_f32 v123, v152, v159
	global_store_dwordx4 v[112:113], v[120:123], off
	v_cvt_pk_bf16_f32 v118, v160, v117
	v_cvt_pk_bf16_f32 v119, v164, v119
	v_mul_f32_e32 v105, v105, v163
	v_mul_f32_e32 v106, v106, v163
	v_cvt_pk_bf16_f32 v120, v161, v162
	v_cvt_pk_bf16_f32 v121, v165, v115
	v_mul_f32_e32 v115, v104, v104
	v_max_f32_e32 v104, v109, v109
	v_max_f32_e32 v104, 0, v104
	v_mul_f32_e32 v109, v105, v105
	v_max_f32_e32 v105, v110, v110
	v_mul_f32_e32 v110, v106, v106
	v_max_f32_e32 v106, v111, v111
	global_store_dwordx4 v[112:113], v[118:121], off offset:256
	v_mul_f32_e32 v104, v104, v163
	v_max_f32_e32 v105, 0, v105
	v_lshlrev_b64 v[118:119], 13, v[124:125]
	v_max_f32_e32 v106, 0, v106
	v_lshl_add_u64 v[118:119], s[92:93], 0, v[118:119]
	v_mul_f32_e32 v108, v108, v163
	v_mul_f32_e32 v104, v104, v104
	v_mul_f32_e32 v105, v105, v163
	v_mul_f32_e32 v106, v106, v163
	v_mul_f32_e32 v107, v107, v163
	v_lshl_add_u64 v[118:119], v[118:119], 0, v[150:151]
	v_mul_f32_e32 v108, v108, v108
	v_mul_f32_e32 v105, v105, v105
	v_mul_f32_e32 v106, v106, v106
	v_mul_f32_e32 v107, v107, v107
	v_cvt_pk_bf16_f32 v104, v108, v104
	v_mul_f32_e32 v96, v96, v163
	v_mul_f32_e32 v97, v97, v163
	v_mul_f32_e32 v98, v98, v163
	v_cvt_pk_bf16_f32 v105, v105, v106
	v_cvt_pk_bf16_f32 v106, v115, v109
	v_cvt_pk_bf16_f32 v107, v110, v107
	global_store_dwordx4 v[118:119], v[104:107], off
	v_mul_f32_e32 v100, v100, v163
	v_mul_f32_e32 v99, v99, v163
	v_mul_f32_e32 v104, v96, v96
	v_max_f32_e32 v96, v101, v101
	v_mul_f32_e32 v101, v97, v97
	v_max_f32_e32 v97, v102, v102
	v_mul_f32_e32 v102, v98, v98
	v_max_f32_e32 v98, v103, v103
	v_max_f32_e32 v96, 0, v96
	v_max_f32_e32 v97, 0, v97
	v_max_f32_e32 v98, 0, v98
	v_mul_f32_e32 v96, v96, v163
	v_mul_f32_e32 v97, v97, v163
	v_mul_f32_e32 v98, v98, v163
	v_mul_f32_e32 v96, v96, v96
	v_mul_f32_e32 v97, v97, v97
	v_mul_f32_e32 v98, v98, v98
	v_mul_f32_e32 v100, v100, v100
	v_mul_f32_e32 v99, v99, v99
	v_cvt_pk_bf16_f32 v96, v100, v96
	v_cvt_pk_bf16_f32 v97, v97, v98
	v_cvt_pk_bf16_f32 v98, v104, v101
	v_mul_f32_e32 v88, v88, v172
	v_cvt_pk_bf16_f32 v99, v102, v99
	global_store_dwordx4 v[118:119], v[96:99], off offset:256
	v_mul_f32_e32 v89, v89, v172
	v_mul_f32_e32 v90, v90, v172
	v_mul_f32_e32 v98, v88, v88
	v_max_f32_e32 v88, v93, v93
	v_max_f32_e32 v88, 0, v88
	v_mul_f32_e32 v93, v89, v89
	v_max_f32_e32 v89, v94, v94
	v_mul_f32_e32 v94, v90, v90
	v_max_f32_e32 v90, v95, v95
	v_lshlrev_b64 v[96:97], 13, v[126:127]
	v_mul_f32_e32 v88, v88, v172
	v_max_f32_e32 v89, 0, v89
	v_max_f32_e32 v90, 0, v90
	v_max_f32_e32 v82, v82, v82
	v_lshl_add_u64 v[96:97], s[92:93], 0, v[96:97]
	v_mul_f32_e32 v92, v92, v172
	v_mul_f32_e32 v88, v88, v88
	v_mul_f32_e32 v89, v89, v172
	v_mul_f32_e32 v90, v90, v172
	v_mul_f32_e32 v91, v91, v172
	v_max_f32_e32 v80, 0, v80
	v_max_f32_e32 v81, 0, v81
	v_max_f32_e32 v82, 0, v82
	v_lshl_add_u64 v[96:97], v[96:97], 0, v[150:151]
	v_mul_f32_e32 v92, v92, v92
	v_mul_f32_e32 v89, v89, v89
	v_mul_f32_e32 v90, v90, v90
	v_mul_f32_e32 v91, v91, v91
	v_cvt_pk_bf16_f32 v88, v92, v88
	v_mul_f32_e32 v80, v80, v172
	v_mul_f32_e32 v81, v81, v172
	v_mul_f32_e32 v82, v82, v172
	v_cvt_pk_bf16_f32 v89, v89, v90
	v_cvt_pk_bf16_f32 v90, v98, v93
	v_cvt_pk_bf16_f32 v91, v94, v91
	global_store_dwordx4 v[96:97], v[88:91], off
	v_max_f32_e32 v84, v84, v84
	v_max_f32_e32 v83, v83, v83
	v_mul_f32_e32 v88, v80, v80
	v_max_f32_e32 v80, v85, v85
	v_mul_f32_e32 v85, v81, v81
	v_max_f32_e32 v81, v86, v86
	v_mul_f32_e32 v86, v82, v82
	v_max_f32_e32 v82, v87, v87
	v_max_f32_e32 v80, 0, v80
	v_max_f32_e32 v81, 0, v81
	v_max_f32_e32 v82, 0, v82
	v_max_f32_e32 v84, 0, v84
	v_mul_f32_e32 v80, v80, v172
	v_mul_f32_e32 v81, v81, v172
	v_mul_f32_e32 v82, v82, v172
	v_max_f32_e32 v83, 0, v83
	v_max_f32_e32 v72, v72, v72
	v_mul_f32_e32 v84, v84, v172
	v_mul_f32_e32 v80, v80, v80
	v_mul_f32_e32 v81, v81, v81
	v_mul_f32_e32 v83, v83, v172
	v_mul_f32_e32 v82, v82, v82
	v_max_f32_e32 v72, 0, v72
	v_max_f32_e32 v73, v73, v73
	v_max_f32_e32 v74, v74, v74
	v_mul_f32_e32 v84, v84, v84
	v_mul_f32_e32 v83, v83, v83
	v_cvt_pk_bf16_f32 v80, v84, v80
	v_cvt_pk_bf16_f32 v81, v81, v82
	v_cvt_pk_bf16_f32 v82, v88, v85
	v_mul_f32_e32 v72, v72, v173
	v_max_f32_e32 v73, 0, v73
	v_max_f32_e32 v74, 0, v74
	v_cvt_pk_bf16_f32 v83, v86, v83
	global_store_dwordx4 v[96:97], v[80:83], off offset:256
	v_mul_f32_e32 v73, v73, v173
	v_mul_f32_e32 v74, v74, v173
	v_mul_f32_e32 v82, v72, v72
	v_max_f32_e32 v72, v77, v77
	v_max_f32_e32 v76, v76, v76
	v_max_f32_e32 v72, 0, v72
	v_mul_f32_e32 v77, v73, v73
	v_max_f32_e32 v73, v78, v78
	v_mul_f32_e32 v78, v74, v74
	v_max_f32_e32 v74, v79, v79
	v_max_f32_e32 v75, v75, v75
	v_lshlrev_b64 v[80:81], 13, v[156:157]
	v_max_f32_e32 v76, 0, v76
	v_mul_f32_e32 v72, v72, v173
	v_max_f32_e32 v73, 0, v73
	v_max_f32_e32 v74, 0, v74
	v_max_f32_e32 v75, 0, v75
	v_max_f32_e32 v64, v64, v64
	v_max_f32_e32 v65, v65, v65
	v_max_f32_e32 v66, v66, v66
	v_lshl_add_u64 v[80:81], s[92:93], 0, v[80:81]
	v_mul_f32_e32 v76, v76, v173
	v_mul_f32_e32 v72, v72, v72
	v_mul_f32_e32 v73, v73, v173
	v_mul_f32_e32 v74, v74, v173
	v_mul_f32_e32 v75, v75, v173
	v_max_f32_e32 v64, 0, v64
	v_max_f32_e32 v65, 0, v65
	v_max_f32_e32 v66, 0, v66
	v_lshl_add_u64 v[80:81], v[80:81], 0, v[150:151]
	v_mul_f32_e32 v76, v76, v76
	v_mul_f32_e32 v73, v73, v73
	v_mul_f32_e32 v74, v74, v74
	v_mul_f32_e32 v75, v75, v75
	v_cvt_pk_bf16_f32 v72, v76, v72
	v_mul_f32_e32 v64, v64, v173
	v_mul_f32_e32 v65, v65, v173
	v_mul_f32_e32 v66, v66, v173
	v_cvt_pk_bf16_f32 v73, v73, v74
	v_cvt_pk_bf16_f32 v74, v82, v77
	v_cvt_pk_bf16_f32 v75, v78, v75
	global_store_dwordx4 v[80:81], v[72:75], off
	v_max_f32_e32 v68, v68, v68
	v_max_f32_e32 v67, v67, v67
	v_mul_f32_e32 v72, v64, v64
	v_max_f32_e32 v64, v69, v69
	v_mul_f32_e32 v69, v65, v65
	v_max_f32_e32 v65, v70, v70
	v_mul_f32_e32 v70, v66, v66
	v_max_f32_e32 v66, v71, v71
	v_max_f32_e32 v64, 0, v64
	v_max_f32_e32 v65, 0, v65
	v_max_f32_e32 v66, 0, v66
	v_max_f32_e32 v68, 0, v68
	v_mul_f32_e32 v64, v64, v173
	v_mul_f32_e32 v65, v65, v173
	v_mul_f32_e32 v66, v66, v173
	v_max_f32_e32 v67, 0, v67
	v_max_f32_e32 v56, v56, v56
	v_mul_f32_e32 v68, v68, v173
	v_mul_f32_e32 v64, v64, v64
	v_mul_f32_e32 v65, v65, v65
	v_mul_f32_e32 v67, v67, v173
	v_mul_f32_e32 v66, v66, v66
	v_max_f32_e32 v56, 0, v56
	v_max_f32_e32 v57, v57, v57
	v_max_f32_e32 v58, v58, v58
	v_mul_f32_e32 v68, v68, v68
	v_mul_f32_e32 v67, v67, v67
	v_cvt_pk_bf16_f32 v64, v68, v64
	v_cvt_pk_bf16_f32 v65, v65, v66
	v_cvt_pk_bf16_f32 v66, v72, v69
	v_mul_f32_e32 v56, v56, v154
	v_max_f32_e32 v57, 0, v57
	v_max_f32_e32 v58, 0, v58
	v_cvt_pk_bf16_f32 v67, v70, v67
	global_store_dwordx4 v[80:81], v[64:67], off offset:256
	v_max_f32_e32 v60, v60, v60
	v_mul_f32_e32 v57, v57, v154
	v_mul_f32_e32 v66, v56, v56
	v_max_f32_e32 v56, v61, v61
	v_mul_f32_e32 v58, v58, v154
	v_max_f32_e32 v60, 0, v60
	v_max_f32_e32 v56, 0, v56
	v_mul_f32_e32 v61, v57, v57
	v_max_f32_e32 v57, v62, v62
	v_mul_f32_e32 v62, v58, v58
	v_max_f32_e32 v58, v63, v63
	v_mul_f32_e32 v60, v60, v154
	v_mul_f32_e32 v56, v56, v154
	v_max_f32_e32 v57, 0, v57
	v_max_f32_e32 v58, 0, v58
	v_max_f32_e32 v59, v59, v59
	v_mul_f32_e32 v60, v60, v60
	v_mul_f32_e32 v56, v56, v56
	v_mul_f32_e32 v57, v57, v154
	v_mul_f32_e32 v58, v58, v154
	v_max_f32_e32 v59, 0, v59
	v_max_f32_e32 v48, v48, v48
	v_max_f32_e32 v49, v49, v49
	v_max_f32_e32 v50, v50, v50
	v_mul_f32_e32 v57, v57, v57
	v_mul_f32_e32 v59, v59, v154
	v_mul_f32_e32 v58, v58, v58
	v_cvt_pk_bf16_f32 v56, v60, v56
	v_add_co_u32_e32 v60, vcc, s54, v112
	v_max_f32_e32 v48, 0, v48
	v_max_f32_e32 v49, 0, v49
	v_max_f32_e32 v50, 0, v50
	v_mul_f32_e32 v59, v59, v59
	v_cvt_pk_bf16_f32 v57, v57, v58
	v_cvt_pk_bf16_f32 v58, v66, v61
	v_addc_co_u32_e32 v61, vcc, 0, v113, vcc
	v_mul_f32_e32 v48, v48, v154
	v_mul_f32_e32 v49, v49, v154
	v_mul_f32_e32 v50, v50, v154
	v_cvt_pk_bf16_f32 v59, v62, v59
	global_store_dwordx4 v[60:61], v[56:59], off
	v_max_f32_e32 v52, v52, v52
	v_max_f32_e32 v51, v51, v51
	v_mul_f32_e32 v56, v48, v48
	v_max_f32_e32 v48, v53, v53
	v_mul_f32_e32 v53, v49, v49
	v_max_f32_e32 v49, v54, v54
	v_mul_f32_e32 v54, v50, v50
	v_max_f32_e32 v50, v55, v55
	v_max_f32_e32 v48, 0, v48
	v_max_f32_e32 v49, 0, v49
	v_max_f32_e32 v50, 0, v50
	v_max_f32_e32 v52, 0, v52
	v_mul_f32_e32 v48, v48, v154
	v_mul_f32_e32 v49, v49, v154
	v_mul_f32_e32 v50, v50, v154
	v_max_f32_e32 v51, 0, v51
	v_max_f32_e32 v40, v40, v40
	v_mul_f32_e32 v52, v52, v154
	v_mul_f32_e32 v48, v48, v48
	v_mul_f32_e32 v49, v49, v49
	v_mul_f32_e32 v51, v51, v154
	v_mul_f32_e32 v50, v50, v50
	v_max_f32_e32 v40, 0, v40
	v_max_f32_e32 v41, v41, v41
	v_max_f32_e32 v42, v42, v42
	v_lshl_add_u64 v[64:65], v[112:113], 0, s[10:11]
	v_mul_f32_e32 v52, v52, v52
	v_mul_f32_e32 v51, v51, v51
	v_cvt_pk_bf16_f32 v48, v52, v48
	v_cvt_pk_bf16_f32 v49, v49, v50
	v_cvt_pk_bf16_f32 v50, v56, v53
	v_mul_f32_e32 v40, v40, v155
	v_max_f32_e32 v41, 0, v41
	v_max_f32_e32 v42, 0, v42
	v_cvt_pk_bf16_f32 v51, v54, v51
	global_store_dwordx4 v[64:65], v[48:51], off offset:256
	v_max_f32_e32 v44, v44, v44
	v_mul_f32_e32 v41, v41, v155
	v_mul_f32_e32 v50, v40, v40
	v_max_f32_e32 v40, v45, v45
	v_mul_f32_e32 v42, v42, v155
	v_max_f32_e32 v44, 0, v44
	v_max_f32_e32 v40, 0, v40
	v_mul_f32_e32 v45, v41, v41
	v_max_f32_e32 v41, v46, v46
	v_mul_f32_e32 v46, v42, v42
	v_max_f32_e32 v42, v47, v47
	v_mul_f32_e32 v44, v44, v155
	v_mul_f32_e32 v40, v40, v155
	v_max_f32_e32 v41, 0, v41
	v_max_f32_e32 v42, 0, v42
	v_max_f32_e32 v43, v43, v43
	v_mul_f32_e32 v44, v44, v44
	v_mul_f32_e32 v40, v40, v40
	v_mul_f32_e32 v41, v41, v155
	v_mul_f32_e32 v42, v42, v155
	v_max_f32_e32 v43, 0, v43
	v_max_f32_e32 v32, v32, v32
	v_max_f32_e32 v33, v33, v33
	v_max_f32_e32 v34, v34, v34
	v_mul_f32_e32 v41, v41, v41
	v_mul_f32_e32 v43, v43, v155
	v_mul_f32_e32 v42, v42, v42
	v_cvt_pk_bf16_f32 v40, v44, v40
	v_add_co_u32_e32 v44, vcc, s55, v112
	v_max_f32_e32 v32, 0, v32
	v_max_f32_e32 v33, 0, v33
	v_max_f32_e32 v34, 0, v34
	v_mul_f32_e32 v43, v43, v43
	v_cvt_pk_bf16_f32 v41, v41, v42
	v_cvt_pk_bf16_f32 v42, v50, v45
	v_addc_co_u32_e32 v45, vcc, 0, v113, vcc
	v_mul_f32_e32 v32, v32, v155
	v_mul_f32_e32 v33, v33, v155
	v_mul_f32_e32 v34, v34, v155
	v_cvt_pk_bf16_f32 v43, v46, v43
	global_store_dwordx4 v[44:45], v[40:43], off
	v_max_f32_e32 v36, v36, v36
	v_max_f32_e32 v35, v35, v35
	v_mul_f32_e32 v40, v32, v32
	v_max_f32_e32 v32, v37, v37
	v_mul_f32_e32 v37, v33, v33
	v_max_f32_e32 v33, v38, v38
	v_mul_f32_e32 v38, v34, v34
	v_max_f32_e32 v34, v39, v39
	v_max_f32_e32 v32, 0, v32
	v_max_f32_e32 v33, 0, v33
	v_max_f32_e32 v34, 0, v34
	v_max_f32_e32 v36, 0, v36
	v_mul_f32_e32 v32, v32, v155
	v_mul_f32_e32 v33, v33, v155
	v_mul_f32_e32 v34, v34, v155
	v_max_f32_e32 v35, 0, v35
	v_max_f32_e32 v24, v24, v24
	v_mul_f32_e32 v36, v36, v155
	v_mul_f32_e32 v32, v32, v32
	v_mul_f32_e32 v33, v33, v33
	v_mul_f32_e32 v35, v35, v155
	v_mul_f32_e32 v34, v34, v34
	v_max_f32_e32 v24, 0, v24
	v_max_f32_e32 v25, v25, v25
	v_max_f32_e32 v26, v26, v26
	v_lshl_add_u64 v[48:49], v[112:113], 0, s[18:19]
	v_mul_f32_e32 v36, v36, v36
	v_mul_f32_e32 v35, v35, v35
	v_cvt_pk_bf16_f32 v32, v36, v32
	v_cvt_pk_bf16_f32 v33, v33, v34
	v_cvt_pk_bf16_f32 v34, v40, v37
	v_mul_f32_e32 v24, v24, v116
	v_max_f32_e32 v25, 0, v25
	v_max_f32_e32 v26, 0, v26
	v_cvt_pk_bf16_f32 v35, v38, v35
	global_store_dwordx4 v[48:49], v[32:35], off offset:256
	v_max_f32_e32 v28, v28, v28
	v_mul_f32_e32 v25, v25, v116
	v_mul_f32_e32 v34, v24, v24
	v_max_f32_e32 v24, v29, v29
	v_mul_f32_e32 v26, v26, v116
	v_max_f32_e32 v28, 0, v28
	v_max_f32_e32 v24, 0, v24
	v_mul_f32_e32 v29, v25, v25
	v_max_f32_e32 v25, v30, v30
	v_mul_f32_e32 v30, v26, v26
	v_max_f32_e32 v26, v31, v31
	v_mul_f32_e32 v28, v28, v116
	v_mul_f32_e32 v24, v24, v116
	v_max_f32_e32 v25, 0, v25
	v_max_f32_e32 v26, 0, v26
	v_max_f32_e32 v27, v27, v27
	v_mul_f32_e32 v28, v28, v28
	v_mul_f32_e32 v24, v24, v24
	v_mul_f32_e32 v25, v25, v116
	v_mul_f32_e32 v26, v26, v116
	v_max_f32_e32 v27, 0, v27
	v_max_f32_e32 v16, v16, v16
	v_max_f32_e32 v17, v17, v17
	v_max_f32_e32 v18, v18, v18
	v_mul_f32_e32 v25, v25, v25
	v_mul_f32_e32 v27, v27, v116
	v_mul_f32_e32 v26, v26, v26
	v_cvt_pk_bf16_f32 v24, v28, v24
	v_add_co_u32_e32 v28, vcc, s56, v112
	v_max_f32_e32 v16, 0, v16
	v_max_f32_e32 v17, 0, v17
	v_max_f32_e32 v18, 0, v18
	v_mul_f32_e32 v27, v27, v27
	v_cvt_pk_bf16_f32 v25, v25, v26
	v_cvt_pk_bf16_f32 v26, v34, v29
	v_addc_co_u32_e32 v29, vcc, 0, v113, vcc
	v_mul_f32_e32 v16, v16, v116
	v_mul_f32_e32 v17, v17, v116
	v_mul_f32_e32 v18, v18, v116
	v_cvt_pk_bf16_f32 v27, v30, v27
	global_store_dwordx4 v[28:29], v[24:27], off
	v_max_f32_e32 v20, v20, v20
	v_max_f32_e32 v19, v19, v19
	v_mul_f32_e32 v24, v16, v16
	v_max_f32_e32 v16, v21, v21
	v_mul_f32_e32 v21, v17, v17
	v_max_f32_e32 v17, v22, v22
	v_mul_f32_e32 v22, v18, v18
	v_max_f32_e32 v18, v23, v23
	v_max_f32_e32 v16, 0, v16
	v_max_f32_e32 v17, 0, v17
	v_max_f32_e32 v18, 0, v18
	v_max_f32_e32 v20, 0, v20
	v_mul_f32_e32 v16, v16, v116
	v_mul_f32_e32 v17, v17, v116
	v_mul_f32_e32 v18, v18, v116
	v_max_f32_e32 v19, 0, v19
	v_max_f32_e32 v8, v8, v8
	v_mul_f32_e32 v20, v20, v116
	v_mul_f32_e32 v16, v16, v16
	v_mul_f32_e32 v17, v17, v17
	v_mul_f32_e32 v19, v19, v116
	v_mul_f32_e32 v18, v18, v18
	v_max_f32_e32 v8, 0, v8
	v_max_f32_e32 v9, v9, v9
	v_max_f32_e32 v10, v10, v10
	v_lshl_add_u64 v[32:33], v[112:113], 0, s[20:21]
	v_mul_f32_e32 v20, v20, v20
	v_mul_f32_e32 v19, v19, v19
	v_cvt_pk_bf16_f32 v16, v20, v16
	v_cvt_pk_bf16_f32 v17, v17, v18
	v_cvt_pk_bf16_f32 v18, v24, v21
	v_mul_f32_e32 v8, v8, v114
	v_max_f32_e32 v9, 0, v9
	v_max_f32_e32 v10, 0, v10
	v_cvt_pk_bf16_f32 v19, v22, v19
	global_store_dwordx4 v[32:33], v[16:19], off offset:256
	v_max_f32_e32 v12, v12, v12
	v_mul_f32_e32 v9, v9, v114
	v_mul_f32_e32 v18, v8, v8
	v_max_f32_e32 v8, v13, v13
	v_mul_f32_e32 v10, v10, v114
	v_max_f32_e32 v12, 0, v12
	v_max_f32_e32 v8, 0, v8
	v_mul_f32_e32 v13, v9, v9
	v_max_f32_e32 v9, v14, v14
	v_mul_f32_e32 v14, v10, v10
	v_max_f32_e32 v10, v15, v15
	v_mul_f32_e32 v12, v12, v114
	v_mul_f32_e32 v8, v8, v114
	v_max_f32_e32 v9, 0, v9
	v_max_f32_e32 v10, 0, v10
	v_max_f32_e32 v11, v11, v11
	v_mul_f32_e32 v12, v12, v12
	v_mul_f32_e32 v8, v8, v8
	v_mul_f32_e32 v9, v9, v114
	v_mul_f32_e32 v10, v10, v114
	v_max_f32_e32 v11, 0, v11
	v_max_f32_e32 v0, v0, v0
	v_max_f32_e32 v1, v1, v1
	v_max_f32_e32 v2, v2, v2
	v_mul_f32_e32 v9, v9, v9
	v_mul_f32_e32 v11, v11, v114
	v_mul_f32_e32 v10, v10, v10
	v_cvt_pk_bf16_f32 v8, v12, v8
	v_add_co_u32_e32 v12, vcc, s57, v112
	v_max_f32_e32 v0, 0, v0
	v_max_f32_e32 v1, 0, v1
	v_max_f32_e32 v2, 0, v2
	v_mul_f32_e32 v11, v11, v11
	v_cvt_pk_bf16_f32 v9, v9, v10
	v_cvt_pk_bf16_f32 v10, v18, v13
	v_addc_co_u32_e32 v13, vcc, 0, v113, vcc
	v_mul_f32_e32 v0, v0, v114
	v_mul_f32_e32 v1, v1, v114
	v_mul_f32_e32 v2, v2, v114
	v_cvt_pk_bf16_f32 v11, v14, v11
	global_store_dwordx4 v[12:13], v[8:11], off
	v_max_f32_e32 v3, v3, v3
	v_max_f32_e32 v4, v4, v4
	v_mul_f32_e32 v8, v0, v0
	v_max_f32_e32 v0, v5, v5
	v_mul_f32_e32 v5, v1, v1
	v_max_f32_e32 v1, v6, v6
	v_mul_f32_e32 v6, v2, v2
	v_max_f32_e32 v2, v7, v7
	v_max_f32_e32 v0, 0, v0
	v_max_f32_e32 v1, 0, v1
	v_max_f32_e32 v2, 0, v2
	v_max_f32_e32 v3, 0, v3
	v_max_f32_e32 v4, 0, v4
	v_mul_f32_e32 v0, v0, v114
	v_mul_f32_e32 v1, v1, v114
	v_mul_f32_e32 v2, v2, v114
	v_mul_f32_e32 v3, v3, v114
	v_lshl_add_u64 v[16:17], v[112:113], 0, s[22:23]
	v_mul_f32_e32 v4, v4, v114
	v_mul_f32_e32 v0, v0, v0
	v_mul_f32_e32 v1, v1, v1
	v_mul_f32_e32 v2, v2, v2
	v_mul_f32_e32 v3, v3, v3
	s_andn2_b64 vcc, exec, s[4:5]
	s_mov_b64 s[4:5], -1
	v_mul_f32_e32 v4, v4, v4
	v_cvt_pk_bf16_f32 v0, v4, v0
	v_cvt_pk_bf16_f32 v1, v1, v2
	v_cvt_pk_bf16_f32 v2, v8, v5
	v_cvt_pk_bf16_f32 v3, v6, v3
	global_store_dwordx4 v[16:17], v[0:3], off offset:256
	s_cbranch_vccnz .LBB0_1076
	s_andn2_b64 vcc, exec, s[0:1]
	s_cbranch_vccnz .LBB0_1075
	s_branch .LBB0_1075
